# t1 + GQA K-tile LDS writes moved from mid-region to the region end (after the last PV MFMA, vmcnt(4)) so no LDS store interleaves with the reads
# speedup vs baseline: 1.0056x; 1.0056x over previous
.LBB0_739:
	ds_read_b128 v[236:239], v200 offset:49152
	ds_read_b128 v[240:243], v208 offset:49152
	ds_read_b128 v[244:247], v207 offset:49152
	ds_read_b128 v[248:251], v206 offset:49152
	s_add_i32 s6, s14, -3
	s_waitcnt lgkmcnt(3)
	v_mfma_f32_32x32x16_bf16 v[80:95], v[236:239], v[124:127], 0
	ds_read_b128 v[236:239], v205 offset:49152
	v_exp_f32_e32 v158, v158
	v_exp_f32_e32 v159, v159
	v_add_f32_e32 v210, 0, v162
	s_waitcnt lgkmcnt(3)
	v_mfma_f32_32x32x16_bf16 v[80:95], v[240:243], v[120:123], v[80:95]
	ds_read_b128 v[240:243], v204 offset:49152
	v_exp_f32_e32 v156, v156
	v_exp_f32_e32 v157, v157
	v_add_f32_e32 v210, v216, v210
	s_waitcnt lgkmcnt(3)
	v_mfma_f32_32x32x16_bf16 v[80:95], v[244:247], v[116:119], v[80:95]
	ds_read_b128 v[244:247], v202 offset:49152
	v_exp_f32_e32 v150, v150
	v_exp_f32_e32 v151, v151
	v_add_f32_e32 v210, v163, v210
	s_waitcnt lgkmcnt(3)
	v_mfma_f32_32x32x16_bf16 v[80:95], v[248:251], v[112:115], v[80:95]
	ds_read_b128 v[248:251], v201 offset:49152
	v_exp_f32_e32 v148, v148
	v_exp_f32_e32 v149, v149
	v_add_f32_e32 v210, v177, v210
	s_waitcnt lgkmcnt(3)
	v_mfma_f32_32x32x16_bf16 v[80:95], v[236:239], v[108:111], v[80:95]
	ds_read_b128 v[236:239], v200 offset:57344
	v_exp_f32_e32 v146, v146
	v_exp_f32_e32 v147, v147
	v_add_f32_e32 v210, v164, v210
	s_waitcnt lgkmcnt(3)
	v_mfma_f32_32x32x16_bf16 v[80:95], v[240:243], v[104:107], v[80:95]
	ds_read_b128 v[240:243], v208 offset:57344
	v_exp_f32_e32 v160, v160
	v_exp_f32_e32 v161, v161
	v_add_f32_e32 v210, v176, v210
	s_waitcnt lgkmcnt(3)
	v_mfma_f32_32x32x16_bf16 v[80:95], v[244:247], v[100:103], v[80:95]
	ds_read_b128 v[244:247], v207 offset:57344
	v_exp_f32_e32 v154, v154
	v_exp_f32_e32 v155, v155
	v_add_f32_e32 v210, v165, v210
	s_waitcnt lgkmcnt(3)
	v_mfma_f32_32x32x16_bf16 v[80:95], v[248:251], v[96:99], v[80:95]
	ds_read_b128 v[248:251], v206 offset:57344
	v_exp_f32_e32 v152, v152
	v_exp_f32_e32 v153, v153
	v_add_f32_e32 v210, v175, v210
	s_waitcnt lgkmcnt(3)
	v_mfma_f32_32x32x16_bf16 v[64:79], v[236:239], v[124:127], 0
	ds_read_b128 v[236:239], v205 offset:57344
	v_add_f32_e32 v210, v166, v210
	v_add_f32_e32 v210, v173, v210
	v_add_f32_e32 v210, v167, v210
	v_add_f32_e32 v210, v172, v210
	v_add_f32_e32 v210, v168, v210
	s_waitcnt lgkmcnt(3)
	v_mfma_f32_32x32x16_bf16 v[64:79], v[240:243], v[120:123], v[64:79]
	ds_read_b128 v[240:243], v204 offset:57344
	v_add_f32_e32 v210, v171, v210
	v_add_f32_e32 v210, v169, v210
	v_add_f32_e32 v210, v170, v210
	v_add_f32_e32 v210, v158, v210
	v_add_f32_e32 v210, v159, v210
	s_waitcnt lgkmcnt(3)
	v_mfma_f32_32x32x16_bf16 v[64:79], v[244:247], v[116:119], v[64:79]
	ds_read_b128 v[244:247], v202 offset:57344
	v_add_f32_e32 v210, v156, v210
	v_add_f32_e32 v210, v157, v210
	v_add_f32_e32 v210, v150, v210
	v_add_f32_e32 v210, v151, v210
	v_add_f32_e32 v210, v148, v210
	s_waitcnt lgkmcnt(3)
	v_mfma_f32_32x32x16_bf16 v[64:79], v[248:251], v[112:115], v[64:79]
	ds_read_b128 v[248:251], v201 offset:57344
	v_add_f32_e32 v210, v149, v210
	v_add_f32_e32 v210, v146, v210
	v_add_f32_e32 v210, v147, v210
	v_add_f32_e32 v210, v160, v210
	v_add_f32_e32 v210, v161, v210
	s_waitcnt lgkmcnt(3)
	v_mfma_f32_32x32x16_bf16 v[64:79], v[236:239], v[108:111], v[64:79]
	v_add_f32_e32 v210, v154, v210
	v_add_f32_e32 v210, v155, v210
	v_add_f32_e32 v210, v152, v210
	v_add_f32_e32 v210, v153, v210
	v_mov_b32_e32 v211, v210
	s_waitcnt lgkmcnt(2)
	v_mfma_f32_32x32x16_bf16 v[64:79], v[240:243], v[104:107], v[64:79]
	v_cvt_pk_bf16_f32 v162, v162, v216
	v_cvt_pk_bf16_f32 v163, v163, v177
	v_cvt_pk_bf16_f32 v164, v164, v176
	v_permlane32_swap_b32_e32 v210, v211
	v_cvt_pk_bf16_f32 v165, v165, v175
	ds_read_b64_tr_b16 v[216:217], v193 offset:0
	ds_read_b64_tr_b16 v[218:219], v193 offset:0x800
	ds_read_b64_tr_b16 v[220:221], v193 offset:0x1000
	ds_read_b64_tr_b16 v[222:223], v193 offset:0x1800
	ds_read_b64_tr_b16 v[224:225], v193 offset:0x2000
	ds_read_b64_tr_b16 v[226:227], v193 offset:0x2800
	ds_read_b64_tr_b16 v[232:233], v193 offset:0x3000
	ds_read_b64_tr_b16 v[234:235], v193 offset:0x3800
	s_waitcnt lgkmcnt(9)
	v_mfma_f32_32x32x16_bf16 v[64:79], v[244:247], v[100:103], v[64:79]
	v_permlane32_swap_b32_e32 v162, v164
	v_cvt_pk_bf16_f32 v166, v166, v173
	v_cvt_pk_bf16_f32 v167, v167, v172
	v_cvt_pk_bf16_f32 v168, v168, v171
	v_cvt_pk_bf16_f32 v169, v169, v170
	s_waitcnt lgkmcnt(8)
	v_mfma_f32_32x32x16_bf16 v[64:79], v[248:251], v[96:99], v[64:79]
	v_cvt_pk_bf16_f32 v170, v158, v159
	v_cvt_pk_bf16_f32 v171, v156, v157
	v_cvt_pk_bf16_f32 v172, v150, v151
	v_cvt_pk_bf16_f32 v173, v148, v149
	v_cvt_pk_bf16_f32 v212, v146, v147
	s_sub_i32 s7, s8, 64
	s_cmp_lt_u32 s6, 2
	s_cselect_b32 s6, s15, s7
	s_ashr_i32 s7, s6, 31
	s_mul_hi_u32 s100, s6, s40
	s_mul_i32 s101, s6, s41
	s_add_u32 s100, s100, s101
	s_mul_i32 s101, s7, s40
	s_add_u32 s100, s100, s101
	s_mul_i32 s6, s6, s40
	s_mov_b32 s7, s100
	s_lshl_b64 s[6:7], s[6:7], 1
	v_permlane32_swap_b32_e32 v163, v165
	s_waitcnt lgkmcnt(6)
	s_nop 0
	v_mfma_f32_32x32x16_bf16 v[48:63], v[162:165], v[216:219], v[48:63]
	ds_read_b64_tr_b16 v[216:217], v193 offset:0x200
	ds_read_b64_tr_b16 v[218:219], v193 offset:0xa00
	v_cvt_pk_bf16_f32 v213, v160, v161
	v_cvt_pk_bf16_f32 v214, v154, v155
	v_cvt_pk_bf16_f32 v215, v152, v153
	v_permlane32_swap_b32_e32 v166, v168
	v_permlane32_swap_b32_e32 v167, v169
	s_waitcnt lgkmcnt(6)
	s_nop 0
	v_mfma_f32_32x32x16_bf16 v[48:63], v[166:169], v[220:223], v[48:63]
	ds_read_b64_tr_b16 v[220:221], v193 offset:0x1200
	ds_read_b64_tr_b16 v[222:223], v193 offset:0x1a00
	v_permlane32_swap_b32_e32 v170, v172
	v_permlane32_swap_b32_e32 v171, v173
	v_permlane32_swap_b32_e32 v212, v214
	v_permlane32_swap_b32_e32 v213, v215
	v_lshl_add_u64 v[146:147], s[6:7], 0, v[178:179]
	s_waitcnt lgkmcnt(6)
	v_mfma_f32_32x32x16_bf16 v[48:63], v[170:173], v[224:227], v[48:63]
	ds_read_b64_tr_b16 v[224:225], v193 offset:0x2200
	ds_read_b64_tr_b16 v[226:227], v193 offset:0x2a00
	v_lshl_add_u64 v[150:151], s[6:7], 0, v[180:181]
	v_lshl_add_u64 v[154:155], s[6:7], 0, v[182:183]
	v_lshl_add_u64 v[158:159], s[6:7], 0, v[184:185]
	v_max_f32_e32 v250, v81, v81
	v_max_f32_e32 v251, v80, v80
	s_waitcnt lgkmcnt(6)
	v_mfma_f32_32x32x16_bf16 v[48:63], v[212:215], v[232:235], v[48:63]
	ds_read_b64_tr_b16 v[232:233], v193 offset:0x3200
	ds_read_b64_tr_b16 v[234:235], v193 offset:0x3a00
	v_max_f32_e32 v250, v251, v250
	v_max3_f32 v250, v250, v82, v83
	v_max3_f32 v250, v250, v84, v85
	v_max3_f32 v250, v250, v86, v87
	v_max3_f32 v250, v250, v88, v89
	s_waitcnt lgkmcnt(6)
	v_mfma_f32_32x32x16_bf16 v[32:47], v[162:165], v[216:219], v[32:47]
	ds_read_b64_tr_b16 v[216:217], v193 offset:0x400
	ds_read_b64_tr_b16 v[218:219], v193 offset:0xc00
	v_max3_f32 v250, v250, v90, v91
	v_max3_f32 v250, v250, v92, v93
	v_max3_f32 v250, v250, v94, v95
	v_max3_f32 v250, v250, v64, v65
	v_max3_f32 v250, v250, v66, v67
	s_waitcnt lgkmcnt(6)
	v_mfma_f32_32x32x16_bf16 v[32:47], v[166:169], v[220:223], v[32:47]
	ds_read_b64_tr_b16 v[220:221], v193 offset:0x1400
	ds_read_b64_tr_b16 v[222:223], v193 offset:0x1c00
	v_max3_f32 v250, v250, v68, v69
	v_max3_f32 v250, v250, v70, v71
	v_max3_f32 v250, v250, v72, v73
	v_max3_f32 v250, v250, v74, v75
	v_max3_f32 v250, v250, v76, v77
	global_load_dwordx4 v[146:149], v[146:147], off
	global_load_dwordx4 v[150:153], v[150:151], off
	global_load_dwordx4 v[154:157], v[154:155], off
	global_load_dwordx4 v[158:161], v[158:159], off
	s_waitcnt lgkmcnt(6)
	v_mfma_f32_32x32x16_bf16 v[32:47], v[170:173], v[224:227], v[32:47]
	ds_read_b64_tr_b16 v[224:225], v193 offset:0x2400
	ds_read_b64_tr_b16 v[226:227], v193 offset:0x2c00
	v_max3_f32 v250, v250, v78, v79
	v_mov_b32_e32 v251, v250
	s_nop 1
	v_permlane32_swap_b32_e32 v250, v251
	v_max_f32_e32 v251, v251, v251
	v_max_f32_e32 v250, v250, v250
	s_waitcnt lgkmcnt(6)
	v_mfma_f32_32x32x16_bf16 v[32:47], v[212:215], v[232:235], v[32:47]
	ds_read_b64_tr_b16 v[232:233], v193 offset:0x3400
	ds_read_b64_tr_b16 v[234:235], v193 offset:0x3c00
	v_max_f32_e32 v250, v250, v251
	v_sub_f32_e32 v251, v250, v174
	v_cmp_ge_f32_e32 vcc, s93, v251
	v_max_f32_e32 v251, v174, v174
	v_max_f32_e32 v250, v251, v250
	s_waitcnt lgkmcnt(6)
	v_mfma_f32_32x32x16_bf16 v[16:31], v[162:165], v[216:219], v[16:31]
	ds_read_b64_tr_b16 v[216:217], v193 offset:0x600
	ds_read_b64_tr_b16 v[218:219], v193 offset:0xe00
	v_sub_f32_e32 v251, v174, v250
	v_mul_f32_e32 v251, 0x3e0293ee, v251
	v_exp_f32_e32 v251, v251
	s_waitcnt lgkmcnt(6)
	v_mfma_f32_32x32x16_bf16 v[16:31], v[166:169], v[220:223], v[16:31]
	ds_read_b64_tr_b16 v[220:221], v193 offset:0x1600
	ds_read_b64_tr_b16 v[222:223], v193 offset:0x1e00
	s_waitcnt lgkmcnt(6)
	v_mfma_f32_32x32x16_bf16 v[16:31], v[170:173], v[224:227], v[16:31]
	ds_read_b64_tr_b16 v[224:225], v193 offset:0x2600
	ds_read_b64_tr_b16 v[226:227], v193 offset:0x2e00
	s_waitcnt lgkmcnt(6)
	v_mfma_f32_32x32x16_bf16 v[16:31], v[212:215], v[232:235], v[16:31]
	ds_read_b64_tr_b16 v[232:233], v193 offset:0x3600
	ds_read_b64_tr_b16 v[234:235], v193 offset:0x3e00
	s_waitcnt lgkmcnt(6)
	v_mfma_f32_32x32x16_bf16 v[0:15], v[162:165], v[216:219], v[0:15]
	s_waitcnt lgkmcnt(4)
	v_mfma_f32_32x32x16_bf16 v[0:15], v[166:169], v[220:223], v[0:15]
	s_waitcnt lgkmcnt(2)
	v_mfma_f32_32x32x16_bf16 v[0:15], v[170:173], v[224:227], v[0:15]
	s_waitcnt lgkmcnt(0)
	v_mfma_f32_32x32x16_bf16 v[0:15], v[212:215], v[232:235], v[0:15]
	s_waitcnt vmcnt(4)
	ds_write_b128 v198, v[136:139] offset:32768
	ds_write_b128 v199, v[140:143] offset:32768
	s_cmp_eq_u64 vcc, exec
	s_cselect_b64 s[6:7], -1, 0
	s_waitcnt lgkmcnt(0)
	s_branch .Lgqa_joinA
.Lgqa_loopA:
	ds_read_b128 v[236:239], v200 offset:49152
	ds_read_b128 v[240:243], v208 offset:49152
	ds_read_b128 v[244:247], v207 offset:49152
	ds_read_b128 v[248:251], v206 offset:49152
	s_add_i32 s6, s14, -3
	s_waitcnt lgkmcnt(3)
	v_mfma_f32_32x32x16_bf16 v[80:95], v[236:239], v[124:127], 0
	ds_read_b128 v[236:239], v205 offset:49152
	v_exp_f32_e32 v162, v162
	v_exp_f32_e32 v216, v216
	v_fma_f32 v158, v64, s92, v152
	v_fma_f32 v159, v65, s92, v152
	s_waitcnt lgkmcnt(3)
	v_mfma_f32_32x32x16_bf16 v[80:95], v[240:243], v[120:123], v[80:95]
	ds_read_b128 v[240:243], v204 offset:49152
	v_exp_f32_e32 v163, v163
	v_exp_f32_e32 v177, v177
	v_fma_f32 v156, v66, s92, v152
	v_fma_f32 v157, v67, s92, v152
	s_waitcnt lgkmcnt(3)
	v_mfma_f32_32x32x16_bf16 v[80:95], v[244:247], v[116:119], v[80:95]
	ds_read_b128 v[244:247], v202 offset:49152
	v_exp_f32_e32 v164, v164
	v_exp_f32_e32 v176, v176
	v_fma_f32 v150, v68, s92, v152
	v_fma_f32 v151, v69, s92, v152
	s_waitcnt lgkmcnt(3)
	v_mfma_f32_32x32x16_bf16 v[80:95], v[248:251], v[112:115], v[80:95]
	ds_read_b128 v[248:251], v201 offset:49152
	v_exp_f32_e32 v165, v165
	v_exp_f32_e32 v175, v175
	v_fma_f32 v148, v70, s92, v152
	v_fma_f32 v149, v71, s92, v152
	s_waitcnt lgkmcnt(3)
	v_mfma_f32_32x32x16_bf16 v[80:95], v[236:239], v[108:111], v[80:95]
	ds_read_b128 v[236:239], v200 offset:57344
	v_exp_f32_e32 v166, v166
	v_exp_f32_e32 v173, v173
	v_fma_f32 v146, v72, s92, v152
	v_fma_f32 v147, v73, s92, v152
	s_waitcnt lgkmcnt(3)
	v_mfma_f32_32x32x16_bf16 v[80:95], v[240:243], v[104:107], v[80:95]
	ds_read_b128 v[240:243], v208 offset:57344
	v_exp_f32_e32 v167, v167
	v_exp_f32_e32 v172, v172
	v_fma_f32 v160, v74, s92, v152
	v_fma_f32 v161, v75, s92, v152
	s_waitcnt lgkmcnt(3)
	v_mfma_f32_32x32x16_bf16 v[80:95], v[244:247], v[100:103], v[80:95]
	ds_read_b128 v[244:247], v207 offset:57344
	v_exp_f32_e32 v168, v168
	v_exp_f32_e32 v171, v171
	v_fma_f32 v154, v76, s92, v152
	v_fma_f32 v155, v77, s92, v152
	s_waitcnt lgkmcnt(3)
	v_mfma_f32_32x32x16_bf16 v[80:95], v[248:251], v[96:99], v[80:95]
	ds_read_b128 v[248:251], v206 offset:57344
	v_exp_f32_e32 v169, v169
	v_exp_f32_e32 v170, v170
	v_fma_f32 v153, v79, s92, v152
	v_fma_f32 v152, v78, s92, v152
	s_waitcnt lgkmcnt(3)
	v_mfma_f32_32x32x16_bf16 v[64:79], v[236:239], v[124:127], 0
	ds_read_b128 v[236:239], v205 offset:57344
	v_exp_f32_e32 v158, v158
	v_exp_f32_e32 v159, v159
	v_add_f32_e32 v210, 0, v162
	s_waitcnt lgkmcnt(3)
	v_mfma_f32_32x32x16_bf16 v[64:79], v[240:243], v[120:123], v[64:79]
	ds_read_b128 v[240:243], v204 offset:57344
	v_exp_f32_e32 v156, v156
	v_exp_f32_e32 v157, v157
	v_add_f32_e32 v210, v216, v210
	s_waitcnt lgkmcnt(3)
	v_mfma_f32_32x32x16_bf16 v[64:79], v[244:247], v[116:119], v[64:79]
	ds_read_b128 v[244:247], v202 offset:57344
	v_exp_f32_e32 v150, v150
	v_exp_f32_e32 v151, v151
	v_add_f32_e32 v210, v163, v210
	s_waitcnt lgkmcnt(3)
	v_mfma_f32_32x32x16_bf16 v[64:79], v[248:251], v[112:115], v[64:79]
	ds_read_b128 v[248:251], v201 offset:57344
	v_exp_f32_e32 v148, v148
	v_exp_f32_e32 v149, v149
	v_add_f32_e32 v210, v177, v210
	s_waitcnt lgkmcnt(3)
	v_mfma_f32_32x32x16_bf16 v[64:79], v[236:239], v[108:111], v[64:79]
	v_exp_f32_e32 v146, v146
	v_exp_f32_e32 v147, v147
	v_add_f32_e32 v210, v164, v210
	s_waitcnt lgkmcnt(2)
	v_mfma_f32_32x32x16_bf16 v[64:79], v[240:243], v[104:107], v[64:79]
	v_exp_f32_e32 v160, v160
	v_exp_f32_e32 v161, v161
	v_add_f32_e32 v210, v176, v210
	s_waitcnt lgkmcnt(1)
	v_mfma_f32_32x32x16_bf16 v[64:79], v[244:247], v[100:103], v[64:79]
	v_exp_f32_e32 v154, v154
	v_exp_f32_e32 v155, v155
	v_add_f32_e32 v210, v165, v210
	s_waitcnt lgkmcnt(0)
	v_mfma_f32_32x32x16_bf16 v[64:79], v[248:251], v[96:99], v[64:79]
	v_exp_f32_e32 v152, v152
	v_exp_f32_e32 v153, v153
	v_add_f32_e32 v210, v175, v210
	s_sub_i32 s7, s8, 64
	s_cmp_lt_u32 s6, 2
	s_cselect_b32 s6, s15, s7
	s_ashr_i32 s7, s6, 31
	s_mul_hi_u32 s100, s6, s40
	s_mul_i32 s101, s6, s41
	s_add_u32 s100, s100, s101
	s_mul_i32 s101, s7, s40
	s_add_u32 s100, s100, s101
	s_mul_i32 s6, s6, s40
	s_mov_b32 s7, s100
	s_lshl_b64 s[6:7], s[6:7], 1
	v_cvt_pk_bf16_f32 v162, v162, v216
	v_cvt_pk_bf16_f32 v163, v163, v177
	v_cvt_pk_bf16_f32 v164, v164, v176
	v_cvt_pk_bf16_f32 v165, v165, v175
	s_nop 0
	v_permlane32_swap_b32_e32 v162, v164
	v_permlane32_swap_b32_e32 v163, v165
	ds_read_b64_tr_b16 v[216:217], v193 offset:0
	ds_read_b64_tr_b16 v[218:219], v193 offset:0x800
	s_waitcnt lgkmcnt(0)
	v_mfma_f32_32x32x16_bf16 v[48:63], v[162:165], v[216:219], v[48:63]
	ds_read_b64_tr_b16 v[220:221], v193 offset:0x1000
	ds_read_b64_tr_b16 v[222:223], v193 offset:0x1800
	ds_read_b64_tr_b16 v[224:225], v193 offset:0x2000
	ds_read_b64_tr_b16 v[226:227], v193 offset:0x2800
	ds_read_b64_tr_b16 v[232:233], v193 offset:0x3000
	ds_read_b64_tr_b16 v[234:235], v193 offset:0x3800
	ds_read_b64_tr_b16 v[216:217], v193 offset:0x200
	ds_read_b64_tr_b16 v[218:219], v193 offset:0xa00
	v_add_f32_e32 v210, v166, v210
	v_add_f32_e32 v210, v173, v210
	v_add_f32_e32 v210, v167, v210
	v_add_f32_e32 v210, v172, v210
	v_add_f32_e32 v210, v168, v210
	v_add_f32_e32 v210, v171, v210
	v_add_f32_e32 v210, v169, v210
	v_cvt_pk_bf16_f32 v166, v166, v173
	v_cvt_pk_bf16_f32 v167, v167, v172
	v_cvt_pk_bf16_f32 v168, v168, v171
	v_cvt_pk_bf16_f32 v169, v169, v170
	s_nop 0
	v_permlane32_swap_b32_e32 v166, v168
	v_permlane32_swap_b32_e32 v167, v169
	s_waitcnt lgkmcnt(6)
	s_nop 0
	v_mfma_f32_32x32x16_bf16 v[48:63], v[166:169], v[220:223], v[48:63]
	ds_read_b64_tr_b16 v[220:221], v193 offset:0x1200
	ds_read_b64_tr_b16 v[222:223], v193 offset:0x1a00
	v_add_f32_e32 v210, v170, v210
	v_add_f32_e32 v210, v158, v210
	v_add_f32_e32 v210, v159, v210
	v_add_f32_e32 v210, v156, v210
	v_add_f32_e32 v210, v157, v210
	v_cvt_pk_bf16_f32 v170, v158, v159
	v_cvt_pk_bf16_f32 v171, v156, v157
	v_cvt_pk_bf16_f32 v172, v150, v151
	v_cvt_pk_bf16_f32 v173, v148, v149
	s_nop 0
	v_permlane32_swap_b32_e32 v170, v172
	v_permlane32_swap_b32_e32 v171, v173
	s_waitcnt lgkmcnt(6)
	s_nop 0
	v_mfma_f32_32x32x16_bf16 v[48:63], v[170:173], v[224:227], v[48:63]
	ds_read_b64_tr_b16 v[224:225], v193 offset:0x2200
	ds_read_b64_tr_b16 v[226:227], v193 offset:0x2a00
	v_add_f32_e32 v210, v150, v210
	v_add_f32_e32 v210, v151, v210
	v_add_f32_e32 v210, v148, v210
	v_add_f32_e32 v210, v149, v210
	v_add_f32_e32 v210, v146, v210
	v_cvt_pk_bf16_f32 v212, v146, v147
	v_cvt_pk_bf16_f32 v213, v160, v161
	v_cvt_pk_bf16_f32 v214, v154, v155
	v_cvt_pk_bf16_f32 v215, v152, v153
	s_nop 0
	v_permlane32_swap_b32_e32 v212, v214
	v_permlane32_swap_b32_e32 v213, v215
	s_waitcnt lgkmcnt(6)
	s_nop 0
	v_mfma_f32_32x32x16_bf16 v[48:63], v[212:215], v[232:235], v[48:63]
	ds_read_b64_tr_b16 v[232:233], v193 offset:0x3200
	ds_read_b64_tr_b16 v[234:235], v193 offset:0x3a00
	v_add_f32_e32 v210, v147, v210
	v_add_f32_e32 v210, v160, v210
	v_add_f32_e32 v210, v161, v210
	v_add_f32_e32 v210, v154, v210
	v_add_f32_e32 v210, v155, v210
	s_waitcnt lgkmcnt(6)
	v_mfma_f32_32x32x16_bf16 v[32:47], v[162:165], v[216:219], v[32:47]
	ds_read_b64_tr_b16 v[216:217], v193 offset:0x400
	ds_read_b64_tr_b16 v[218:219], v193 offset:0xc00
	v_add_f32_e32 v210, v152, v210
	v_add_f32_e32 v210, v153, v210
	v_mov_b32_e32 v211, v210
	s_nop 1
	v_permlane32_swap_b32_e32 v210, v211
	v_lshl_add_u64 v[146:147], s[6:7], 0, v[178:179]
	s_waitcnt lgkmcnt(6)
	v_mfma_f32_32x32x16_bf16 v[32:47], v[166:169], v[220:223], v[32:47]
	ds_read_b64_tr_b16 v[220:221], v193 offset:0x1400
	ds_read_b64_tr_b16 v[222:223], v193 offset:0x1c00
	v_lshl_add_u64 v[150:151], s[6:7], 0, v[180:181]
	v_lshl_add_u64 v[154:155], s[6:7], 0, v[182:183]
	v_lshl_add_u64 v[158:159], s[6:7], 0, v[184:185]
	v_max_f32_e32 v250, v81, v81
	v_max_f32_e32 v251, v80, v80
	global_load_dwordx4 v[146:149], v[146:147], off
	global_load_dwordx4 v[150:153], v[150:151], off
	global_load_dwordx4 v[154:157], v[154:155], off
	global_load_dwordx4 v[158:161], v[158:159], off
	s_waitcnt lgkmcnt(6)
	v_mfma_f32_32x32x16_bf16 v[32:47], v[170:173], v[224:227], v[32:47]
	ds_read_b64_tr_b16 v[224:225], v193 offset:0x2400
	ds_read_b64_tr_b16 v[226:227], v193 offset:0x2c00
	v_max_f32_e32 v250, v251, v250
	v_max3_f32 v250, v250, v82, v83
	v_max3_f32 v250, v250, v84, v85
	v_max3_f32 v250, v250, v86, v87
	v_max3_f32 v250, v250, v88, v89
	s_waitcnt lgkmcnt(6)
	v_mfma_f32_32x32x16_bf16 v[32:47], v[212:215], v[232:235], v[32:47]
	ds_read_b64_tr_b16 v[232:233], v193 offset:0x3400
	ds_read_b64_tr_b16 v[234:235], v193 offset:0x3c00
	v_max3_f32 v250, v250, v90, v91
	v_max3_f32 v250, v250, v92, v93
	v_max3_f32 v250, v250, v94, v95
	v_max3_f32 v250, v250, v64, v65
	v_max3_f32 v250, v250, v66, v67
	s_waitcnt lgkmcnt(6)
	v_mfma_f32_32x32x16_bf16 v[16:31], v[162:165], v[216:219], v[16:31]
	ds_read_b64_tr_b16 v[216:217], v193 offset:0x600
	ds_read_b64_tr_b16 v[218:219], v193 offset:0xe00
	v_max3_f32 v250, v250, v68, v69
	v_max3_f32 v250, v250, v70, v71
	v_max3_f32 v250, v250, v72, v73
	v_max3_f32 v250, v250, v74, v75
	v_max3_f32 v250, v250, v76, v77
	s_waitcnt lgkmcnt(6)
	v_mfma_f32_32x32x16_bf16 v[16:31], v[166:169], v[220:223], v[16:31]
	ds_read_b64_tr_b16 v[220:221], v193 offset:0x1600
	ds_read_b64_tr_b16 v[222:223], v193 offset:0x1e00
	v_max3_f32 v250, v250, v78, v79
	v_mov_b32_e32 v251, v250
	s_nop 1
	v_permlane32_swap_b32_e32 v250, v251
	v_max_f32_e32 v251, v251, v251
	v_max_f32_e32 v250, v250, v250
	s_waitcnt lgkmcnt(6)
	v_mfma_f32_32x32x16_bf16 v[16:31], v[170:173], v[224:227], v[16:31]
	ds_read_b64_tr_b16 v[224:225], v193 offset:0x2600
	ds_read_b64_tr_b16 v[226:227], v193 offset:0x2e00
	v_max_f32_e32 v250, v250, v251
	v_sub_f32_e32 v251, v250, v174
	v_cmp_ge_f32_e32 vcc, s93, v251
	v_max_f32_e32 v251, v174, v174
	v_max_f32_e32 v250, v251, v250
	s_waitcnt lgkmcnt(6)
	v_mfma_f32_32x32x16_bf16 v[16:31], v[212:215], v[232:235], v[16:31]
	ds_read_b64_tr_b16 v[232:233], v193 offset:0x3600
	ds_read_b64_tr_b16 v[234:235], v193 offset:0x3e00
	v_sub_f32_e32 v251, v174, v250
	v_mul_f32_e32 v251, 0x3e0293ee, v251
	v_exp_f32_e32 v251, v251
	s_waitcnt lgkmcnt(6)
	v_mfma_f32_32x32x16_bf16 v[0:15], v[162:165], v[216:219], v[0:15]
	s_waitcnt lgkmcnt(4)
	v_mfma_f32_32x32x16_bf16 v[0:15], v[166:169], v[220:223], v[0:15]
	s_waitcnt lgkmcnt(2)
	v_mfma_f32_32x32x16_bf16 v[0:15], v[170:173], v[224:227], v[0:15]
	s_waitcnt lgkmcnt(0)
	v_mfma_f32_32x32x16_bf16 v[0:15], v[212:215], v[232:235], v[0:15]
	s_waitcnt vmcnt(4)
	ds_write_b128 v198, v[136:139] offset:32768
	ds_write_b128 v199, v[140:143] offset:32768
	s_cmp_eq_u64 vcc, exec
	s_cselect_b64 s[6:7], -1, 0
	s_waitcnt lgkmcnt(0)

.LBB0_743:
	v_cndmask_b32_e64 v216, v250, v174, s[6:7]
	v_mul_f32_e32 v212, 0xbe0293ee, v216
	v_fmamk_f32 v162, v80, 0x3e0293ee, v212
	v_fmamk_f32 v177, v81, 0x3e0293ee, v212
	v_fmamk_f32 v163, v82, 0x3e0293ee, v212
	v_fmamk_f32 v176, v83, 0x3e0293ee, v212
	v_fmamk_f32 v164, v84, 0x3e0293ee, v212
	v_fmamk_f32 v175, v85, 0x3e0293ee, v212
	v_fmamk_f32 v165, v86, 0x3e0293ee, v212
	v_fmamk_f32 v174, v87, 0x3e0293ee, v212
	v_fmamk_f32 v166, v88, 0x3e0293ee, v212
	v_fmamk_f32 v173, v89, 0x3e0293ee, v212
	v_fmamk_f32 v167, v90, 0x3e0293ee, v212
	v_fmamk_f32 v172, v91, 0x3e0293ee, v212
	v_fmamk_f32 v168, v92, 0x3e0293ee, v212
	v_fmamk_f32 v171, v93, 0x3e0293ee, v212
	v_fmamk_f32 v169, v94, 0x3e0293ee, v212
	v_fmamk_f32 v170, v95, 0x3e0293ee, v212
	ds_read_b128 v[240:243], v200 offset:32768
	ds_read_b128 v[244:247], v208 offset:32768
	ds_read_b128 v[248:251], v207 offset:32768
	s_waitcnt lgkmcnt(2)
	v_mfma_f32_32x32x16_bf16 v[80:95], v[240:243], v[124:127], 0
	ds_read_b128 v[240:243], v206 offset:32768
	v_exp_f32_e32 v162, v162
	v_exp_f32_e32 v177, v177
	v_fmamk_f32 v219, v70, 0x3e0293ee, v212
	s_waitcnt lgkmcnt(2)
	v_mfma_f32_32x32x16_bf16 v[80:95], v[244:247], v[120:123], v[80:95]
	ds_read_b128 v[244:247], v205 offset:32768
	v_exp_f32_e32 v163, v163
	v_exp_f32_e32 v176, v176
	v_fmamk_f32 v220, v71, 0x3e0293ee, v212
	s_waitcnt lgkmcnt(2)
	v_mfma_f32_32x32x16_bf16 v[80:95], v[248:251], v[116:119], v[80:95]
	ds_read_b128 v[248:251], v204 offset:32768
	v_exp_f32_e32 v164, v164
	v_exp_f32_e32 v175, v175
	v_fmamk_f32 v225, v64, 0x3e0293ee, v212
	s_waitcnt lgkmcnt(2)
	v_mfma_f32_32x32x16_bf16 v[80:95], v[240:243], v[112:115], v[80:95]
	ds_read_b128 v[240:243], v202 offset:32768
	v_exp_f32_e32 v165, v165
	v_exp_f32_e32 v174, v174
	v_fmamk_f32 v226, v65, 0x3e0293ee, v212
	s_waitcnt lgkmcnt(2)
	v_mfma_f32_32x32x16_bf16 v[80:95], v[244:247], v[108:111], v[80:95]
	ds_read_b128 v[244:247], v201 offset:32768
	v_exp_f32_e32 v166, v166
	v_exp_f32_e32 v173, v173
	v_fmamk_f32 v227, v66, 0x3e0293ee, v212
	s_waitcnt lgkmcnt(2)
	v_mfma_f32_32x32x16_bf16 v[80:95], v[248:251], v[104:107], v[80:95]
	ds_read_b128 v[248:251], v200 offset:40960
	v_exp_f32_e32 v167, v167
	v_exp_f32_e32 v172, v172
	v_fmamk_f32 v232, v67, 0x3e0293ee, v212
	s_waitcnt lgkmcnt(2)
	v_mfma_f32_32x32x16_bf16 v[80:95], v[240:243], v[100:103], v[80:95]
	ds_read_b128 v[240:243], v208 offset:40960
	v_exp_f32_e32 v168, v168
	v_exp_f32_e32 v171, v171
	v_fmamk_f32 v233, v68, 0x3e0293ee, v212
	s_waitcnt lgkmcnt(2)
	v_mfma_f32_32x32x16_bf16 v[80:95], v[244:247], v[96:99], v[80:95]
	ds_read_b128 v[244:247], v207 offset:40960
	v_exp_f32_e32 v169, v169
	v_exp_f32_e32 v170, v170
	v_fmamk_f32 v218, v69, 0x3e0293ee, v212
	v_fmamk_f32 v221, v72, 0x3e0293ee, v212
	v_fmamk_f32 v222, v73, 0x3e0293ee, v212
	v_fmamk_f32 v223, v74, 0x3e0293ee, v212
	v_fmamk_f32 v224, v75, 0x3e0293ee, v212
	v_fmamk_f32 v213, v76, 0x3e0293ee, v212
	v_fmamk_f32 v234, v77, 0x3e0293ee, v212
	v_fmamk_f32 v235, v78, 0x3e0293ee, v212
	v_fmac_f32_e32 v212, 0x3e0293ee, v79
	s_waitcnt lgkmcnt(2)
	v_mfma_f32_32x32x16_bf16 v[64:79], v[248:251], v[124:127], 0
	ds_read_b128 v[248:251], v206 offset:40960
	v_exp_f32_e32 v215, v226
	v_exp_f32_e32 v226, v232
	s_waitcnt lgkmcnt(2)
	v_mfma_f32_32x32x16_bf16 v[64:79], v[240:243], v[120:123], v[64:79]
	ds_read_b128 v[240:243], v205 offset:40960
	v_exp_f32_e32 v232, v219
	v_add_f32_e32 v219, 0, v162
	v_add_f32_e32 v219, v177, v219
	v_add_f32_e32 v219, v163, v219
	s_waitcnt lgkmcnt(2)
	v_mfma_f32_32x32x16_bf16 v[64:79], v[244:247], v[116:119], v[64:79]
	ds_read_b128 v[244:247], v204 offset:40960
	v_add_f32_e32 v219, v176, v219
	v_add_f32_e32 v219, v164, v219
	v_add_f32_e32 v219, v175, v219
	v_add_f32_e32 v219, v165, v219
	v_add_f32_e32 v219, v174, v219
	s_waitcnt lgkmcnt(2)
	v_mfma_f32_32x32x16_bf16 v[64:79], v[248:251], v[112:115], v[64:79]
	ds_read_b128 v[248:251], v202 offset:40960
	v_add_f32_e32 v219, v166, v219
	v_add_f32_e32 v219, v173, v219
	v_add_f32_e32 v219, v167, v219
	v_add_f32_e32 v219, v172, v219
	v_add_f32_e32 v219, v168, v219
	s_waitcnt lgkmcnt(2)
	v_mfma_f32_32x32x16_bf16 v[64:79], v[240:243], v[108:111], v[64:79]
	ds_read_b128 v[240:243], v201 offset:40960
	v_exp_f32_e32 v214, v225
	v_add_f32_e32 v219, v171, v219
	v_exp_f32_e32 v225, v227
	s_waitcnt lgkmcnt(2)
	v_mfma_f32_32x32x16_bf16 v[64:79], v[244:247], v[104:107], v[64:79]
	v_add_f32_e32 v219, v169, v219
	v_add_f32_e32 v219, v170, v219
	v_exp_f32_e32 v227, v233
	v_add_f32_e32 v219, v214, v219
	s_waitcnt lgkmcnt(1)
	v_mfma_f32_32x32x16_bf16 v[64:79], v[248:251], v[100:103], v[64:79]
	v_exp_f32_e32 v218, v218
	v_add_f32_e32 v219, v215, v219
	v_add_f32_e32 v219, v225, v219
	v_add_f32_e32 v219, v226, v219
	s_waitcnt lgkmcnt(0)
	v_mfma_f32_32x32x16_bf16 v[64:79], v[240:243], v[96:99], v[64:79]
	v_exp_f32_e32 v233, v220
	v_exp_f32_e32 v221, v221
	v_add_f32_e32 v219, v227, v219
	s_cmp_ge_u32 s14, s91
	s_cselect_b64 s[10:11], -1, 0
	s_ashr_i32 s9, s8, 31
	s_mul_hi_u32 s100, s8, s40
	s_mul_i32 s101, s8, s41
	s_add_u32 s100, s100, s101
	s_mul_i32 s101, s9, s40
	s_add_u32 s100, s100, s101
	s_mul_i32 s6, s8, s40
	s_mov_b32 s7, s100
	s_lshl_b64 s[6:7], s[6:7], 1
	v_exp_f32_e32 v222, v222
	v_add_f32_e32 v219, v218, v219
	v_exp_f32_e32 v223, v223
	v_add_f32_e32 v219, v232, v219
	v_exp_f32_e32 v224, v224
	v_add_f32_e32 v219, v233, v219
	v_exp_f32_e32 v213, v213
	v_add_f32_e32 v219, v221, v219
	v_exp_f32_e32 v234, v234
	v_add_f32_e32 v219, v222, v219
	v_exp_f32_e32 v235, v235
	v_add_f32_e32 v219, v223, v219
	v_exp_f32_e32 v212, v212
	v_add_f32_e32 v219, v224, v219
	v_add_f32_e32 v219, v213, v219
	v_add_f32_e32 v219, v234, v219
	v_add_f32_e32 v219, v235, v219
	v_add_f32_e32 v219, v212, v219
	v_cvt_pk_bf16_f32 v162, v162, v177
	v_cvt_pk_bf16_f32 v163, v163, v176
	v_cvt_pk_bf16_f32 v164, v164, v175
	v_cvt_pk_bf16_f32 v165, v165, v174
	v_cvt_pk_bf16_f32 v169, v169, v170
	v_cvt_pk_bf16_f32 v170, v214, v215
	v_cvt_pk_bf16_f32 v176, v213, v234
	v_cvt_pk_bf16_f32 v177, v235, v212
	v_permlane32_swap_b32_e32 v162, v164
	v_permlane32_swap_b32_e32 v163, v165
	ds_read_b64_tr_b16 v[212:213], v197 offset:0
	ds_read_b64_tr_b16 v[214:215], v197 offset:0x800
	s_waitcnt lgkmcnt(0)
	v_mfma_f32_32x32x16_bf16 v[48:63], v[162:165], v[212:215], v[48:63]
	v_mov_b32_e32 v220, v219
	s_nop 1
	v_permlane32_swap_b32_e32 v219, v220
	v_cvt_pk_bf16_f32 v166, v166, v173
	v_cvt_pk_bf16_f32 v167, v167, v172
	v_cvt_pk_bf16_f32 v168, v168, v171
	v_cvt_pk_bf16_f32 v171, v225, v226
	v_cvt_pk_bf16_f32 v174, v221, v222
	v_cvt_pk_bf16_f32 v175, v223, v224
	v_permlane32_swap_b32_e32 v166, v168
	v_permlane32_swap_b32_e32 v167, v169
	ds_read_b64_tr_b16 v[222:223], v197 offset:0x1000
	ds_read_b64_tr_b16 v[224:225], v197 offset:0x1800
	s_waitcnt lgkmcnt(0)
	v_mfma_f32_32x32x16_bf16 v[48:63], v[166:169], v[222:225], v[48:63]
	v_cvt_pk_bf16_f32 v172, v227, v218
	v_cvt_pk_bf16_f32 v173, v232, v233
	s_nop 0
	v_permlane32_swap_b32_e32 v170, v172
	v_permlane32_swap_b32_e32 v171, v173
	v_permlane32_swap_b32_e32 v174, v176
	ds_read_b64_tr_b16 v[232:233], v197 offset:0x2000
	ds_read_b64_tr_b16 v[234:235], v197 offset:0x2800
	ds_read_b64_tr_b16 v[236:237], v197 offset:0x3000
	ds_read_b64_tr_b16 v[238:239], v197 offset:0x3800
	ds_read_b64_tr_b16 v[212:213], v197 offset:0x200
	ds_read_b64_tr_b16 v[214:215], v197 offset:0xa00
	ds_read_b64_tr_b16 v[222:223], v197 offset:0x1200
	ds_read_b64_tr_b16 v[224:225], v197 offset:0x1a00
	s_waitcnt lgkmcnt(6)
	v_mfma_f32_32x32x16_bf16 v[48:63], v[170:173], v[232:235], v[48:63]
	ds_read_b64_tr_b16 v[232:233], v197 offset:0x2200
	ds_read_b64_tr_b16 v[234:235], v197 offset:0x2a00
	v_permlane32_swap_b32_e32 v175, v177
	v_lshl_add_u64 v[128:129], s[6:7], 0, v[178:179]
	v_lshl_add_u64 v[132:133], s[6:7], 0, v[180:181]
	v_lshl_add_u64 v[136:137], s[6:7], 0, v[182:183]
	v_lshl_add_u64 v[140:141], s[6:7], 0, v[184:185]
	s_waitcnt lgkmcnt(6)
	v_mfma_f32_32x32x16_bf16 v[48:63], v[174:177], v[236:239], v[48:63]
	ds_read_b64_tr_b16 v[236:237], v197 offset:0x3200
	ds_read_b64_tr_b16 v[238:239], v197 offset:0x3a00
	v_max_f32_e32 v250, v81, v81
	v_max_f32_e32 v251, v80, v80
	v_max_f32_e32 v250, v251, v250
	v_max3_f32 v250, v250, v82, v83
	v_max3_f32 v250, v250, v84, v85
	s_waitcnt lgkmcnt(6)
	v_mfma_f32_32x32x16_bf16 v[32:47], v[162:165], v[212:215], v[32:47]
	ds_read_b64_tr_b16 v[212:213], v197 offset:0x400
	ds_read_b64_tr_b16 v[214:215], v197 offset:0xc00
	v_max3_f32 v250, v250, v86, v87
	v_max3_f32 v250, v250, v88, v89
	v_max3_f32 v250, v250, v90, v91
	v_max3_f32 v250, v250, v92, v93
	v_max3_f32 v250, v250, v94, v95
	s_waitcnt lgkmcnt(6)
	v_mfma_f32_32x32x16_bf16 v[32:47], v[166:169], v[222:225], v[32:47]
	ds_read_b64_tr_b16 v[222:223], v197 offset:0x1400
	ds_read_b64_tr_b16 v[224:225], v197 offset:0x1c00
	v_max3_f32 v250, v250, v64, v65
	v_max3_f32 v250, v250, v66, v67
	v_max3_f32 v250, v250, v68, v69
	v_max3_f32 v250, v250, v70, v71
	v_max3_f32 v250, v250, v72, v73
	global_load_dwordx4 v[128:131], v[128:129], off
	global_load_dwordx4 v[132:135], v[132:133], off
	global_load_dwordx4 v[136:139], v[136:137], off
	global_load_dwordx4 v[140:143], v[140:141], off
	s_waitcnt lgkmcnt(6)
	v_mfma_f32_32x32x16_bf16 v[32:47], v[170:173], v[232:235], v[32:47]
	ds_read_b64_tr_b16 v[232:233], v197 offset:0x2400
	ds_read_b64_tr_b16 v[234:235], v197 offset:0x2c00
	v_max3_f32 v250, v250, v74, v75
	v_max3_f32 v250, v250, v76, v77
	v_max3_f32 v250, v250, v78, v79
	v_mov_b32_e32 v251, v250
	s_nop 1
	v_permlane32_swap_b32_e32 v250, v251
	s_waitcnt lgkmcnt(6)
	v_mfma_f32_32x32x16_bf16 v[32:47], v[174:177], v[236:239], v[32:47]
	ds_read_b64_tr_b16 v[236:237], v197 offset:0x3400
	ds_read_b64_tr_b16 v[238:239], v197 offset:0x3c00
	v_max_f32_e32 v251, v251, v251
	v_max_f32_e32 v250, v250, v250
	v_max_f32_e32 v250, v250, v251
	v_sub_f32_e32 v251, v250, v216
	v_cmp_ge_f32_e32 vcc, s93, v251
	s_waitcnt lgkmcnt(6)
	v_mfma_f32_32x32x16_bf16 v[16:31], v[162:165], v[212:215], v[16:31]
	ds_read_b64_tr_b16 v[212:213], v197 offset:0x600
	ds_read_b64_tr_b16 v[214:215], v197 offset:0xe00
	v_max_f32_e32 v251, v216, v216
	v_max_f32_e32 v250, v251, v250
	v_sub_f32_e32 v251, v216, v250
	v_mul_f32_e32 v251, 0x3e0293ee, v251
	s_waitcnt lgkmcnt(6)
	v_mfma_f32_32x32x16_bf16 v[16:31], v[166:169], v[222:225], v[16:31]
	ds_read_b64_tr_b16 v[222:223], v197 offset:0x1600
	ds_read_b64_tr_b16 v[224:225], v197 offset:0x1e00
	v_exp_f32_e32 v251, v251
	s_waitcnt lgkmcnt(6)
	v_mfma_f32_32x32x16_bf16 v[16:31], v[170:173], v[232:235], v[16:31]
	ds_read_b64_tr_b16 v[232:233], v197 offset:0x2600
	ds_read_b64_tr_b16 v[234:235], v197 offset:0x2e00
	s_waitcnt lgkmcnt(6)
	v_mfma_f32_32x32x16_bf16 v[16:31], v[174:177], v[236:239], v[16:31]
	ds_read_b64_tr_b16 v[236:237], v197 offset:0x3600
	ds_read_b64_tr_b16 v[238:239], v197 offset:0x3e00
	s_waitcnt lgkmcnt(6)
	v_mfma_f32_32x32x16_bf16 v[0:15], v[162:165], v[212:215], v[0:15]
	s_waitcnt lgkmcnt(4)
	v_mfma_f32_32x32x16_bf16 v[0:15], v[166:169], v[222:225], v[0:15]
	s_waitcnt lgkmcnt(2)
	v_mfma_f32_32x32x16_bf16 v[0:15], v[170:173], v[232:235], v[0:15]
	s_waitcnt lgkmcnt(0)
	v_mfma_f32_32x32x16_bf16 v[0:15], v[174:177], v[236:239], v[0:15]
	s_waitcnt vmcnt(4)
	ds_write_b128 v198, v[154:157] offset:49152
	ds_write_b128 v199, v[158:161] offset:49152
	s_cmp_eq_u64 vcc, exec
	s_cselect_b64 s[6:7], -1, 0
	s_waitcnt lgkmcnt(0)
	s_barrier
	v_cndmask_b32_e64 v218, v251, 1.0, s[6:7]
	v_cmp_gt_f32_e32 vcc, 1.0, v218
	ds_write_b128 v195, v[146:149] offset:16384
	ds_write_b128 v196, v[150:153] offset:16384
	s_cbranch_vccz .LBB0_749
	s_and_saveexec_b64 s[12:13], s[4:5]
	ds_write_b32 v194, v218 offset:128
	s_or_b64 exec, exec, s[12:13]
	s_waitcnt lgkmcnt(0)
	v_add_u32_e32 v158, v192, v144
	ds_read_b128 v[146:149], v158 offset:224
	ds_read_b128 v[150:153], v158 offset:192
	ds_read_b128 v[154:157], v158 offset:160
	ds_read_b128 v[158:161], v158 offset:128
	s_waitcnt lgkmcnt(3)
	v_pk_mul_f32 v[60:61], v[60:61], v[146:147]
	s_waitcnt lgkmcnt(2)
	v_pk_mul_f32 v[56:57], v[56:57], v[150:151]
	s_waitcnt lgkmcnt(1)
	v_pk_mul_f32 v[52:53], v[52:53], v[154:155]
	v_pk_mul_f32 v[62:63], v[62:63], v[148:149]
	v_pk_mul_f32 v[58:59], v[58:59], v[152:153]
	v_pk_mul_f32 v[54:55], v[54:55], v[156:157]
	s_waitcnt lgkmcnt(0)
	v_pk_mul_f32 v[50:51], v[50:51], v[160:161]
	v_pk_mul_f32 v[48:49], v[48:49], v[158:159]
	v_pk_mul_f32 v[44:45], v[44:45], v[146:147]
	v_pk_mul_f32 v[40:41], v[40:41], v[150:151]
	v_pk_mul_f32 v[36:37], v[36:37], v[154:155]
	v_pk_mul_f32 v[46:47], v[46:47], v[148:149]
	v_pk_mul_f32 v[42:43], v[42:43], v[152:153]
	v_pk_mul_f32 v[38:39], v[38:39], v[156:157]
	v_pk_mul_f32 v[34:35], v[34:35], v[160:161]
	v_pk_mul_f32 v[32:33], v[32:33], v[158:159]
	v_pk_mul_f32 v[28:29], v[28:29], v[146:147]
	v_pk_mul_f32 v[24:25], v[24:25], v[150:151]
	v_pk_mul_f32 v[20:21], v[20:21], v[154:155]
	v_pk_mul_f32 v[30:31], v[30:31], v[148:149]
	v_pk_mul_f32 v[26:27], v[26:27], v[152:153]
	v_pk_mul_f32 v[22:23], v[22:23], v[156:157]
	v_pk_mul_f32 v[18:19], v[18:19], v[160:161]
	v_pk_mul_f32 v[16:17], v[16:17], v[158:159]
	v_pk_mul_f32 v[12:13], v[12:13], v[146:147]
	v_pk_mul_f32 v[8:9], v[8:9], v[150:151]
	v_pk_mul_f32 v[4:5], v[4:5], v[154:155]
	v_pk_mul_f32 v[14:15], v[14:15], v[148:149]
	v_pk_mul_f32 v[10:11], v[10:11], v[152:153]
	v_pk_mul_f32 v[6:7], v[6:7], v[156:157]
	v_pk_mul_f32 v[2:3], v[2:3], v[160:161]
	v_pk_mul_f32 v[0:1], v[0:1], v[158:159]
